# P2 HGRN feature loop: all 32 per-item bf16 loads hoisted to the top of the item into spare registers with counted vmcnt waits (hipcc waited on each pair right after issuing it); hazard slots kept with
# speedup vs baseline: 1.0703x; 1.0275x over previous
; #define PIN(i) (*(const float* const __attribute__((address_space(4)))*)(KA + 8 * (i)))
; DEVI float bf2f(bf16_t h) { return __uint_as_float(((uint32_t)h) << 16); }
; DEVI void phase_p2(const int TIDX, const int BIDX, const int GDIM, KAP KA, unsigned char* WSB, float* OUTB, int l, unsigned char* smem) {
;     ...
;       {
;         const int k = tid & 127, half = tid >> 7, colh = h * 128 + k;
;         float* sB = (float*)(smem + 2 * 32 * 136 * 2);
;         float lb = 0.f;
;         if (l == 1) { const float a0 = PIN(I_HGLB)[colh], a1 = PIN(I_HGLB)[512 + colh]; lb = 1.f / (1.f + expf(a0 - a1)); }
;         const float oml = 1.f - lb;
;         float bt[16], kk[16], qv[16];
;         float bl = 0.f;
; #pragma unroll
;         for (int j = 0; j < 16; ++j) {
;           const size_t row = (size_t)ch * 32 + half * 16 + j;
;           const float z = bf2f(FQ[row * 1024 + colh]);
;           qv[j] = bf2f(FQ[row * 1024 + 512 + colh]);
;           const float e = __expf(-z);
;           const float inv = __builtin_amdgcn_rcpf(1.f + e);
;           const float f = lb + oml * inv;
;           kk[j] = oml * e * inv;
;           bl += __logf(f);
;           bt[j] = bl;
;         }
;         sB[half * 128 + k] = bl;
;         __syncthreads();
.LBB0_380:
	s_ashr_i32 s44, s8, 2
	s_ashr_i32 s45, s44, 31
	v_lshlrev_b32_e32 v128, 1, v2
	v_lshl_add_u64 v[2:3], s[42:43], 0, v[128:129]
	s_lshl_b64 s[44:45], s[44:45], 16
	v_lshl_add_u64 v[2:3], v[2:3], 0, s[44:45]
	v_lshl_add_u64 v[46:47], v[2:3], 0, v[20:21]
	s_waitcnt vmcnt(24)
	s_mov_b64 s[44:45], 0x2000
	v_lshl_add_u64 v[176:177], v[46:47], 0, s[44:45]
	s_mov_b64 s[44:45], 0x4000
	v_lshl_add_u64 v[178:179], v[46:47], 0, s[44:45]
	s_mov_b64 s[44:45], 0x6000
	v_lshl_add_u64 v[180:181], v[46:47], 0, s[44:45]
	s_mov_b64 s[44:45], 0x8000
	v_lshl_add_u64 v[182:183], v[46:47], 0, s[44:45]
	global_load_ushort v142, v[46:47], off
	global_load_ushort v143, v[46:47], off offset:1024
	global_load_ushort v144, v[46:47], off offset:2048
	global_load_ushort v145, v[46:47], off offset:3072
	global_load_ushort v146, v[176:177], off offset:-4096
	global_load_ushort v147, v[176:177], off offset:-3072
	global_load_ushort v148, v[176:177], off offset:-2048
	global_load_ushort v149, v[176:177], off offset:-1024
	global_load_ushort v150, v[176:177], off
	global_load_ushort v151, v[176:177], off offset:1024
	global_load_ushort v152, v[176:177], off offset:2048
	global_load_ushort v153, v[176:177], off offset:3072
	global_load_ushort v154, v[178:179], off offset:-4096
	global_load_ushort v155, v[178:179], off offset:-3072
	global_load_ushort v156, v[178:179], off offset:-2048
	global_load_ushort v157, v[178:179], off offset:-1024
	global_load_ushort v158, v[178:179], off
	global_load_ushort v159, v[178:179], off offset:1024
	global_load_ushort v160, v[178:179], off offset:2048
	global_load_ushort v162, v[178:179], off offset:3072
	global_load_ushort v163, v[180:181], off offset:-4096
	global_load_ushort v164, v[180:181], off offset:-3072
	global_load_ushort v165, v[180:181], off offset:-2048
	global_load_ushort v166, v[180:181], off offset:-1024
	global_load_ushort v167, v[180:181], off
	global_load_ushort v168, v[180:181], off offset:1024
	global_load_ushort v169, v[180:181], off offset:2048
	global_load_ushort v170, v[180:181], off offset:3072
	global_load_ushort v171, v[182:183], off offset:-4096
	global_load_ushort v172, v[182:183], off offset:-3072
	global_load_ushort v173, v[182:183], off offset:-2048
	global_load_ushort v174, v[182:183], off offset:-1024
	s_nop 0
	s_nop 0
	v_sub_f32_e32 v0, 1.0, v51
	s_mov_b32 s75, 0x3f317217
	s_mov_b32 s74, 0x7f800000
	s_movk_i32 s9, 0x1000
	s_waitcnt vmcnt(31)
	v_mov_b32_e32 v1, v142
	v_lshlrev_b32_e32 v1, 16, v1
	v_mul_f32_e32 v1, 0xbfb8aa3b, v1
	v_exp_f32_e32 v8, v1
	s_waitcnt vmcnt(30)
	v_mov_b32_e32 v2, v143
	v_lshlrev_b32_e32 v56, 16, v2
	v_add_f32_e32 v1, 1.0, v8
	v_rcp_f32_e32 v6, v1
	s_nop 0
	v_fma_f32 v1, v0, v6, v51
	v_cmp_gt_f32_e32 vcc, s60, v1
	s_nop 1
	v_cndmask_b32_e64 v2, 0, 32, vcc
	v_ldexp_f32 v1, v1, v2
	v_log_f32_e32 v1, v1
	s_nop 0
	v_mul_f32_e32 v2, 0x3f317217, v1
	v_fma_f32 v2, v1, s75, -v2
	v_fmac_f32_e32 v2, 0x3377d1cf, v1
	v_fmac_f32_e32 v2, 0x3f317217, v1
	v_cmp_lt_f32_e64 s[44:45], |v1|, s74
	s_nop 1
	v_cndmask_b32_e64 v1, v1, v2, s[44:45]
	v_cndmask_b32_e32 v2, 0, v235, vcc
	v_sub_f32_e32 v1, v1, v2
	v_add_f32_e32 v57, 0, v1
	s_nop 0
	s_nop 0
	s_waitcnt vmcnt(29)
	v_mov_b32_e32 v1, v144
	v_lshlrev_b32_e32 v1, 16, v1
	v_mul_f32_e32 v1, 0xbfb8aa3b, v1
	v_exp_f32_e32 v9, v1
	s_waitcnt vmcnt(28)
	v_mov_b32_e32 v2, v145
	v_lshlrev_b32_e32 v79, 16, v2
	v_mul_f32_e32 v103, 0xbfb8aa3b, v79
	v_exp_f32_e32 v103, v103
	v_add_f32_e32 v1, 1.0, v9
	v_rcp_f32_e32 v7, v1
	v_add_f32_e32 v103, 1.0, v103
	v_rcp_f32_e32 v103, v103
	v_fma_f32 v1, v0, v7, v51
	v_cmp_gt_f32_e32 vcc, s60, v1
	v_mul_f32_e32 v79, v103, v79
	s_nop 0
	v_cndmask_b32_e64 v2, 0, 32, vcc
	v_ldexp_f32 v1, v1, v2
	v_log_f32_e32 v1, v1
	s_nop 0
	v_mul_f32_e32 v2, 0x3f317217, v1
	v_fma_f32 v2, v1, s75, -v2
	v_fmac_f32_e32 v2, 0x3377d1cf, v1
	v_fmac_f32_e32 v2, 0x3f317217, v1
	v_cmp_lt_f32_e64 s[44:45], |v1|, s74
	s_nop 1
	v_cndmask_b32_e64 v1, v1, v2, s[44:45]
	v_cndmask_b32_e32 v2, 0, v235, vcc
	v_sub_f32_e32 v1, v1, v2
	v_add_co_u32_e32 v2, vcc, s9, v46
	s_movk_i32 s9, 0x2000
	s_nop 0
	v_addc_co_u32_e32 v3, vcc, 0, v47, vcc
	v_add_co_u32_e32 v4, vcc, s9, v46
	v_add_f32_e32 v86, v57, v1
	s_nop 0
	v_addc_co_u32_e32 v5, vcc, 0, v47, vcc
	s_nop 0
	s_nop 0
	s_movk_i32 s9, 0x3000
	s_waitcnt vmcnt(27)
	v_mov_b32_e32 v1, v146
	v_lshlrev_b32_e32 v1, 16, v1
	v_mul_f32_e32 v1, 0xbfb8aa3b, v1
	v_exp_f32_e32 v36, v1
	s_waitcnt vmcnt(26)
	v_mov_b32_e32 v10, v147
	v_lshlrev_b32_e32 v83, 16, v10
	v_add_f32_e32 v1, 1.0, v36
	v_rcp_f32_e32 v34, v1
	s_nop 0
	v_fma_f32 v1, v0, v34, v51
	v_cmp_gt_f32_e32 vcc, s60, v1
	s_nop 1
	v_cndmask_b32_e64 v10, 0, 32, vcc
	v_ldexp_f32 v1, v1, v10
	v_log_f32_e32 v1, v1
	s_nop 0
	v_mul_f32_e32 v10, 0x3f317217, v1
	v_fma_f32 v10, v1, s75, -v10
	v_fmac_f32_e32 v10, 0x3377d1cf, v1
	v_fmac_f32_e32 v10, 0x3f317217, v1
	v_cmp_lt_f32_e64 s[44:45], |v1|, s74
	s_nop 1
	v_cndmask_b32_e64 v1, v1, v10, s[44:45]
	v_cndmask_b32_e32 v10, 0, v235, vcc
	v_sub_f32_e32 v1, v1, v10
	v_add_f32_e32 v89, v86, v1
	s_nop 0
	s_waitcnt vmcnt(25)
	v_mov_b32_e32 v1, v148
	v_lshlrev_b32_e32 v1, 16, v1
	s_nop 0
	v_mul_f32_e32 v1, 0xbfb8aa3b, v1
	v_exp_f32_e32 v37, v1
	s_waitcnt vmcnt(24)
	v_mov_b32_e32 v2, v149
	v_lshlrev_b32_e32 v88, 16, v2
	v_add_f32_e32 v1, 1.0, v37
	v_rcp_f32_e32 v35, v1
	s_nop 0
	v_fma_f32 v1, v0, v35, v51
	v_cmp_gt_f32_e32 vcc, s60, v1
	s_nop 1
	v_cndmask_b32_e64 v2, 0, 32, vcc
	v_ldexp_f32 v1, v1, v2
	v_log_f32_e32 v1, v1
	s_nop 0
	v_mul_f32_e32 v2, 0x3f317217, v1
	v_fma_f32 v2, v1, s75, -v2
	v_fmac_f32_e32 v2, 0x3377d1cf, v1
	v_fmac_f32_e32 v2, 0x3f317217, v1
	v_cmp_lt_f32_e64 s[44:45], |v1|, s74
	s_nop 1
	v_cndmask_b32_e64 v1, v1, v2, s[44:45]
	v_cndmask_b32_e32 v2, 0, v235, vcc
	v_sub_f32_e32 v1, v1, v2
	v_add_f32_e32 v92, v89, v1
	s_nop 0
	s_nop 0
	s_waitcnt vmcnt(23)
; #define PIN(i) (*(const float* const __attribute__((address_space(4)))*)(KA + 8 * (i)))
; DEVI float bf2f(bf16_t h) { return __uint_as_float(((uint32_t)h) << 16); }
; DEVI void phase_p2(const int TIDX, const int BIDX, const int GDIM, KAP KA, unsigned char* WSB, float* OUTB, int l, unsigned char* smem) {
;     ...
;       {
;         const int k = tid & 127, half = tid >> 7, colh = h * 128 + k;
;         float* sB = (float*)(smem + 2 * 32 * 136 * 2);
;         float lb = 0.f;
;         if (l == 1) { const float a0 = PIN(I_HGLB)[colh], a1 = PIN(I_HGLB)[512 + colh]; lb = 1.f / (1.f + expf(a0 - a1)); }
;         const float oml = 1.f - lb;
;         float bt[16], kk[16], qv[16];
;         float bl = 0.f;
; #pragma unroll
;         for (int j = 0; j < 16; ++j) {
;           const size_t row = (size_t)ch * 32 + half * 16 + j;
;           const float z = bf2f(FQ[row * 1024 + colh]);
;           qv[j] = bf2f(FQ[row * 1024 + 512 + colh]);
;           const float e = __expf(-z);
;           const float inv = __builtin_amdgcn_rcpf(1.f + e);
;           const float f = lb + oml * inv;
;           kk[j] = oml * e * inv;
;           bl += __logf(f);
;           bt[j] = bl;
;         }
;         sB[half * 128 + k] = bl;
;         __syncthreads();
	v_mov_b32_e32 v1, v150
	v_lshlrev_b32_e32 v1, 16, v1
	v_mul_f32_e32 v1, 0xbfb8aa3b, v1
	v_exp_f32_e32 v32, v1
	s_waitcnt vmcnt(22)
	v_mov_b32_e32 v2, v151
	v_lshlrev_b32_e32 v81, 16, v2
	v_add_f32_e32 v1, 1.0, v32
	v_rcp_f32_e32 v14, v1
	s_nop 0
	v_fma_f32 v1, v0, v14, v51
	v_cmp_gt_f32_e32 vcc, s60, v1
	s_nop 1
	v_cndmask_b32_e64 v2, 0, 32, vcc
	v_ldexp_f32 v1, v1, v2
	v_log_f32_e32 v1, v1
	s_nop 0
	v_mul_f32_e32 v2, 0x3f317217, v1
	v_fma_f32 v2, v1, s75, -v2
	v_fmac_f32_e32 v2, 0x3377d1cf, v1
	v_fmac_f32_e32 v2, 0x3f317217, v1
	v_cmp_lt_f32_e64 s[44:45], |v1|, s74
	s_nop 1
	v_cndmask_b32_e64 v1, v1, v2, s[44:45]
	v_cndmask_b32_e32 v2, 0, v235, vcc
	v_sub_f32_e32 v1, v1, v2
	v_add_f32_e32 v87, v92, v1
	s_nop 0
	s_nop 0
	s_waitcnt vmcnt(21)
	v_mov_b32_e32 v1, v152
	v_lshlrev_b32_e32 v1, 16, v1
	v_mul_f32_e32 v1, 0xbfb8aa3b, v1
	v_exp_f32_e32 v33, v1
	s_waitcnt vmcnt(20)
	v_mov_b32_e32 v2, v153
	v_lshlrev_b32_e32 v77, 16, v2
	v_add_f32_e32 v1, 1.0, v33
	v_rcp_f32_e32 v15, v1
	s_nop 0
	v_fma_f32 v1, v0, v15, v51
	v_cmp_gt_f32_e32 vcc, s60, v1
	s_nop 1
	v_cndmask_b32_e64 v2, 0, 32, vcc
	v_ldexp_f32 v1, v1, v2
	v_log_f32_e32 v1, v1
	s_nop 0
	v_mul_f32_e32 v2, 0x3f317217, v1
	v_fma_f32 v2, v1, s75, -v2
	v_fmac_f32_e32 v2, 0x3377d1cf, v1
	v_fmac_f32_e32 v2, 0x3f317217, v1
	v_cmp_lt_f32_e64 s[44:45], |v1|, s74
	s_nop 1
	v_cndmask_b32_e64 v1, v1, v2, s[44:45]
	v_cndmask_b32_e32 v2, 0, v235, vcc
	v_sub_f32_e32 v1, v1, v2
	v_add_co_u32_e32 v2, vcc, s9, v46
	s_movk_i32 s9, 0x4000
	s_nop 0
	v_addc_co_u32_e32 v3, vcc, 0, v47, vcc
	v_add_co_u32_e32 v4, vcc, s9, v46
	v_add_f32_e32 v82, v87, v1
	s_nop 0
	v_addc_co_u32_e32 v5, vcc, 0, v47, vcc
	s_nop 0
	s_nop 0
	s_movk_i32 s9, 0x5000
	s_waitcnt vmcnt(19)
	v_mov_b32_e32 v1, v154
	v_lshlrev_b32_e32 v1, 16, v1
	v_mul_f32_e32 v1, 0xbfb8aa3b, v1
	v_exp_f32_e32 v44, v1
	s_waitcnt vmcnt(18)
	v_mov_b32_e32 v10, v155
	v_lshlrev_b32_e32 v95, 16, v10
	v_add_f32_e32 v1, 1.0, v44
	v_rcp_f32_e32 v42, v1
	s_nop 0
	v_fma_f32 v1, v0, v42, v51
	v_cmp_gt_f32_e32 vcc, s60, v1
	s_nop 1
	v_cndmask_b32_e64 v10, 0, 32, vcc
	v_ldexp_f32 v1, v1, v10
	v_log_f32_e32 v1, v1
	s_nop 0
	v_mul_f32_e32 v10, 0x3f317217, v1
	v_fma_f32 v10, v1, s75, -v10
	v_fmac_f32_e32 v10, 0x3377d1cf, v1
	v_fmac_f32_e32 v10, 0x3f317217, v1
	v_cmp_lt_f32_e64 s[44:45], |v1|, s74
	s_nop 1
	v_cndmask_b32_e64 v1, v1, v10, s[44:45]
	v_cndmask_b32_e32 v10, 0, v235, vcc
	v_sub_f32_e32 v1, v1, v10
	v_add_f32_e32 v97, v82, v1
	s_nop 0
	s_waitcnt vmcnt(17)
	v_mov_b32_e32 v1, v156
	v_lshlrev_b32_e32 v1, 16, v1
	s_nop 0
	v_mul_f32_e32 v1, 0xbfb8aa3b, v1
	v_exp_f32_e32 v45, v1
	s_waitcnt vmcnt(16)
	v_mov_b32_e32 v2, v157
	v_lshlrev_b32_e32 v94, 16, v2
	v_add_f32_e32 v1, 1.0, v45
	v_rcp_f32_e32 v43, v1
	s_nop 0
	v_fma_f32 v1, v0, v43, v51
	v_cmp_gt_f32_e32 vcc, s60, v1
	s_nop 1
	v_cndmask_b32_e64 v2, 0, 32, vcc
	v_ldexp_f32 v1, v1, v2
	v_log_f32_e32 v1, v1
	s_nop 0
	v_mul_f32_e32 v2, 0x3f317217, v1
	v_fma_f32 v2, v1, s75, -v2
	v_fmac_f32_e32 v2, 0x3377d1cf, v1
	v_fmac_f32_e32 v2, 0x3f317217, v1
	v_cmp_lt_f32_e64 s[44:45], |v1|, s74
	s_nop 1
	v_cndmask_b32_e64 v1, v1, v2, s[44:45]
	v_cndmask_b32_e32 v2, 0, v235, vcc
	v_sub_f32_e32 v1, v1, v2
	v_add_f32_e32 v96, v97, v1
	s_nop 0
	s_nop 0
	s_waitcnt vmcnt(15)
	v_mov_b32_e32 v1, v158
	v_lshlrev_b32_e32 v1, 16, v1
	v_mul_f32_e32 v1, 0xbfb8aa3b, v1
	v_exp_f32_e32 v40, v1
	s_waitcnt vmcnt(14)
	v_mov_b32_e32 v2, v159
	v_lshlrev_b32_e32 v90, 16, v2
	v_add_f32_e32 v1, 1.0, v40
	v_rcp_f32_e32 v38, v1
	s_nop 0
	v_fma_f32 v1, v0, v38, v51
	v_cmp_gt_f32_e32 vcc, s60, v1
	s_nop 1
	v_cndmask_b32_e64 v2, 0, 32, vcc
	v_ldexp_f32 v1, v1, v2
	v_log_f32_e32 v1, v1
	s_nop 0
	v_mul_f32_e32 v2, 0x3f317217, v1
	v_fma_f32 v2, v1, s75, -v2
	v_fmac_f32_e32 v2, 0x3377d1cf, v1
	v_fmac_f32_e32 v2, 0x3f317217, v1
	v_cmp_lt_f32_e64 s[44:45], |v1|, s74
	s_nop 1
	v_cndmask_b32_e64 v1, v1, v2, s[44:45]
	v_cndmask_b32_e32 v2, 0, v235, vcc
	v_sub_f32_e32 v1, v1, v2
	v_add_f32_e32 v93, v96, v1
	s_nop 0
	s_nop 0
	s_waitcnt vmcnt(13)
	v_mov_b32_e32 v1, v160
	v_lshlrev_b32_e32 v1, 16, v1
	v_mul_f32_e32 v1, 0xbfb8aa3b, v1
	v_exp_f32_e32 v41, v1
	s_waitcnt vmcnt(12)
	v_mov_b32_e32 v2, v162
	v_lshlrev_b32_e32 v84, 16, v2
	v_add_f32_e32 v1, 1.0, v41
	v_rcp_f32_e32 v39, v1
	s_nop 0
	v_fma_f32 v1, v0, v39, v51
	v_cmp_gt_f32_e32 vcc, s60, v1
	s_nop 1
	v_cndmask_b32_e64 v2, 0, 32, vcc
	v_ldexp_f32 v1, v1, v2
	v_log_f32_e32 v1, v1
	s_nop 0
	v_mul_f32_e32 v2, 0x3f317217, v1
	v_fma_f32 v2, v1, s75, -v2
	v_fmac_f32_e32 v2, 0x3377d1cf, v1
	v_fmac_f32_e32 v2, 0x3f317217, v1
	v_cmp_lt_f32_e64 s[44:45], |v1|, s74
	s_nop 1
	v_cndmask_b32_e64 v1, v1, v2, s[44:45]
	v_cndmask_b32_e32 v2, 0, v235, vcc
	v_sub_f32_e32 v1, v1, v2
	v_add_co_u32_e32 v2, vcc, s9, v46
	s_movk_i32 s9, 0x6000
	s_nop 0
	v_addc_co_u32_e32 v3, vcc, 0, v47, vcc
	v_add_co_u32_e32 v48, vcc, s9, v46
	v_add_f32_e32 v91, v93, v1
	s_nop 0
	v_addc_co_u32_e32 v49, vcc, 0, v47, vcc
	s_nop 0
	s_nop 0
	s_movk_i32 s9, 0x7000
	s_waitcnt vmcnt(11)
	v_mov_b32_e32 v1, v163
	v_lshlrev_b32_e32 v1, 16, v1
	v_mul_f32_e32 v1, 0xbfb8aa3b, v1
	v_exp_f32_e32 v12, v1
	s_waitcnt vmcnt(10)
	v_mov_b32_e32 v4, v164
	v_lshlrev_b32_e32 v78, 16, v4
	v_add_f32_e32 v1, 1.0, v12
	v_rcp_f32_e32 v10, v1
	s_nop 0
	v_fma_f32 v1, v0, v10, v51
	v_cmp_gt_f32_e32 vcc, s60, v1
	s_nop 1
	v_cndmask_b32_e64 v4, 0, 32, vcc
	v_ldexp_f32 v1, v1, v4
	v_log_f32_e32 v1, v1
	s_nop 0
	v_mul_f32_e32 v4, 0x3f317217, v1
	v_fma_f32 v4, v1, s75, -v4
	v_fmac_f32_e32 v4, 0x3377d1cf, v1
	v_fmac_f32_e32 v4, 0x3f317217, v1
	v_cmp_lt_f32_e64 s[44:45], |v1|, s74
	s_nop 1
	v_cndmask_b32_e64 v1, v1, v4, s[44:45]
	v_cndmask_b32_e32 v4, 0, v235, vcc
	v_sub_f32_e32 v1, v1, v4
	v_add_f32_e32 v85, v91, v1
	s_nop 0
	s_waitcnt vmcnt(9)
; #define PIN(i) (*(const float* const __attribute__((address_space(4)))*)(KA + 8 * (i)))
; DEVI float bf2f(bf16_t h) { return __uint_as_float(((uint32_t)h) << 16); }
; DEVI void phase_p2(const int TIDX, const int BIDX, const int GDIM, KAP KA, unsigned char* WSB, float* OUTB, int l, unsigned char* smem) {
;     ...
;       {
;         const int k = tid & 127, half = tid >> 7, colh = h * 128 + k;
;         float* sB = (float*)(smem + 2 * 32 * 136 * 2);
;         float lb = 0.f;
;         if (l == 1) { const float a0 = PIN(I_HGLB)[colh], a1 = PIN(I_HGLB)[512 + colh]; lb = 1.f / (1.f + expf(a0 - a1)); }
;         const float oml = 1.f - lb;
;         float bt[16], kk[16], qv[16];
;         float bl = 0.f;
; #pragma unroll
;         for (int j = 0; j < 16; ++j) {
;           const size_t row = (size_t)ch * 32 + half * 16 + j;
;           const float z = bf2f(FQ[row * 1024 + colh]);
;           qv[j] = bf2f(FQ[row * 1024 + 512 + colh]);
;           const float e = __expf(-z);
;           const float inv = __builtin_amdgcn_rcpf(1.f + e);
;           const float f = lb + oml * inv;
;           kk[j] = oml * e * inv;
;           bl += __logf(f);
;           bt[j] = bl;
;         }
;         sB[half * 128 + k] = bl;
;         __syncthreads();
	v_mov_b32_e32 v1, v165
	v_lshlrev_b32_e32 v1, 16, v1
	s_nop 0
	v_mul_f32_e32 v1, 0xbfb8aa3b, v1
	v_exp_f32_e32 v13, v1
	s_waitcnt vmcnt(8)
	v_mov_b32_e32 v2, v166
	v_lshlrev_b32_e32 v76, 16, v2
	v_add_f32_e32 v1, 1.0, v13
	v_rcp_f32_e32 v11, v1
	s_nop 0
	v_fma_f32 v1, v0, v11, v51
	v_cmp_gt_f32_e32 vcc, s60, v1
	s_nop 1
	v_cndmask_b32_e64 v2, 0, 32, vcc
	v_ldexp_f32 v1, v1, v2
	v_log_f32_e32 v1, v1
	s_nop 0
	v_mul_f32_e32 v2, 0x3f317217, v1
	v_fma_f32 v2, v1, s75, -v2
	v_fmac_f32_e32 v2, 0x3377d1cf, v1
	v_fmac_f32_e32 v2, 0x3f317217, v1
	v_cmp_lt_f32_e64 s[44:45], |v1|, s74
	s_nop 1
	v_cndmask_b32_e64 v1, v1, v2, s[44:45]
	v_cndmask_b32_e32 v2, 0, v235, vcc
	v_sub_f32_e32 v1, v1, v2
	v_add_f32_e32 v80, v85, v1
	s_nop 0
	s_nop 0
	s_waitcnt vmcnt(7)
	v_mov_b32_e32 v1, v167
	v_lshlrev_b32_e32 v1, 16, v1
	v_mul_f32_e32 v1, 0xbfb8aa3b, v1
	v_exp_f32_e32 v4, v1
	s_waitcnt vmcnt(6)
	v_mov_b32_e32 v2, v168
	v_lshlrev_b32_e32 v19, 16, v2
	v_add_f32_e32 v1, 1.0, v4
	v_rcp_f32_e32 v2, v1
	s_nop 0
	v_fma_f32 v1, v0, v2, v51
	v_cmp_gt_f32_e32 vcc, s60, v1
	s_nop 1
	v_cndmask_b32_e64 v3, 0, 32, vcc
	v_ldexp_f32 v1, v1, v3
	v_log_f32_e32 v1, v1
	s_nop 0
	v_mul_f32_e32 v3, 0x3f317217, v1
	v_fma_f32 v3, v1, s75, -v3
	v_fmac_f32_e32 v3, 0x3377d1cf, v1
	v_fmac_f32_e32 v3, 0x3f317217, v1
	v_cmp_lt_f32_e64 s[44:45], |v1|, s74
	s_nop 1
	v_cndmask_b32_e64 v1, v1, v3, s[44:45]
	v_cndmask_b32_e32 v3, 0, v235, vcc
	v_sub_f32_e32 v1, v1, v3
	v_add_f32_e32 v52, v80, v1
	s_nop 0
	s_waitcnt vmcnt(5)
	v_mov_b32_e32 v1, v169
	v_lshlrev_b32_e32 v3, 16, v1
	v_mul_f32_e32 v3, 0xbfb8aa3b, v3
	v_exp_f32_e32 v5, v3
	s_nop 0
	v_add_f32_e32 v3, 1.0, v5
	v_rcp_f32_e32 v3, v3
	s_waitcnt vmcnt(4)
	v_mov_b32_e32 v1, v170
	v_lshlrev_b32_e32 v1, 16, v1
	v_fma_f32 v48, v0, v3, v51
	v_cmp_gt_f32_e32 vcc, s60, v48
	v_pk_mul_f32 v[8:9], v[0:1], v[8:9] op_sel_hi:[0,1]
	v_pk_mul_f32 v[6:7], v[8:9], v[6:7]
	v_cndmask_b32_e64 v49, 0, 32, vcc
	v_ldexp_f32 v48, v48, v49
	v_log_f32_e32 v48, v48
	v_pk_mul_f32 v[32:33], v[0:1], v[32:33] op_sel_hi:[0,1]
	v_pk_mul_f32 v[14:15], v[32:33], v[14:15]
	v_pk_mul_f32 v[12:13], v[0:1], v[12:13] op_sel_hi:[0,1]
	v_mul_f32_e32 v49, 0x3f317217, v48
	v_fma_f32 v49, v48, s75, -v49
	v_fmac_f32_e32 v49, 0x3377d1cf, v48
	v_fmac_f32_e32 v49, 0x3f317217, v48
	v_cmp_lt_f32_e64 s[44:45], |v48|, s74
	v_pk_mul_f32 v[10:11], v[12:13], v[10:11]
	s_nop 0
	v_cndmask_b32_e64 v48, v48, v49, s[44:45]
	v_cndmask_b32_e32 v49, 0, v235, vcc
	v_add_co_u32_e32 v54, vcc, s9, v46
	v_sub_f32_e32 v48, v48, v49
	s_nop 0
	v_addc_co_u32_e32 v55, vcc, 0, v47, vcc
	s_nop 0
	s_nop 0
	v_add_f32_e32 v50, v52, v48
	s_mov_b32 s9, 0x42a00000
	s_waitcnt vmcnt(3)
	v_mov_b32_e32 v46, v171
	v_lshlrev_b32_e32 v46, 16, v46
	v_mul_f32_e32 v46, 0xbfb8aa3b, v46
	v_exp_f32_e32 v48, v46
	s_waitcnt vmcnt(2)
	v_mov_b32_e32 v47, v172
	v_lshlrev_b32_e32 v98, 16, v47
	v_add_f32_e32 v46, 1.0, v48
	v_rcp_f32_e32 v46, v46
	s_nop 0
	v_fma_f32 v47, v0, v46, v51
	v_cmp_gt_f32_e32 vcc, s60, v47
	s_nop 1
	v_cndmask_b32_e64 v49, 0, 32, vcc
	v_ldexp_f32 v47, v47, v49
	v_log_f32_e32 v47, v47
	s_nop 0
	v_mul_f32_e32 v49, 0x3f317217, v47
	v_fma_f32 v49, v47, s75, -v49
	v_fmac_f32_e32 v49, 0x3377d1cf, v47
	v_fmac_f32_e32 v49, 0x3f317217, v47
	v_cmp_lt_f32_e64 s[44:45], |v47|, s74
	s_nop 1
	v_cndmask_b32_e64 v47, v47, v49, s[44:45]
	v_cndmask_b32_e32 v49, 0, v235, vcc
	v_sub_f32_e32 v47, v47, v49
	v_add_f32_e32 v99, v50, v47
	s_nop 0
	s_nop 0
	s_waitcnt vmcnt(1)
	v_mov_b32_e32 v47, v173
	v_lshlrev_b32_e32 v47, 16, v47
	v_mul_f32_e32 v47, 0xbfb8aa3b, v47
	s_waitcnt vmcnt(0)
	v_mov_b32_e32 v49, v174
	v_lshlrev_b32_e32 v100, 16, v49
	v_exp_f32_e32 v49, v47
	s_nop 0
	v_add_f32_e32 v47, 1.0, v49
	v_rcp_f32_e32 v47, v47
	s_nop 0
	v_fmac_f32_e32 v51, v0, v47
	v_cmp_gt_f32_e32 vcc, s60, v51
	s_nop 1
	v_cndmask_b32_e64 v53, 0, 32, vcc
	v_ldexp_f32 v51, v51, v53
	v_log_f32_e32 v51, v51
	s_nop 0
	v_mul_f32_e32 v53, 0x3f317217, v51
	v_fma_f32 v53, v51, s75, -v53
	v_fmac_f32_e32 v53, 0x3377d1cf, v51
	v_fmac_f32_e32 v53, 0x3f317217, v51
	v_cmp_lt_f32_e64 s[44:45], |v51|, s74
	s_nop 1
	v_cndmask_b32_e64 v51, v51, v53, s[44:45]
	v_cndmask_b32_e32 v53, 0, v235, vcc
	v_sub_f32_e32 v51, v51, v53
	v_add_f32_e32 v51, v99, v51
	ds_write_b32 v58, v51 offset:17408
	s_waitcnt lgkmcnt(0)
	s_barrier
; DEVI bf16_t f2bf(float f) { uint32_t u = __float_as_uint(f); u += 0x7fffu + ((u >> 16) & 1u); return (bf16_t)(u >> 16); }
; DEVI void phase_p2(const int TIDX, const int BIDX, const int GDIM, KAP KA, unsigned char* WSB, float* OUTB, int l, unsigned char* smem) {
;     ...
;         const float b0 = sB[k], b1 = sB[128 + k];
;         const float off = half ? b0 : 0.f, bend = b0 + b1;
;         uint32_t pk[8];
; #pragma unroll
;         for (int j = 0; j < 16; ++j) {
;           const int t = half * 16 + j;
;           const float b = bt[j] + off;
;           const float qs = qv[j] * __builtin_amdgcn_rcpf(1.f + __expf(-qv[j]));
;           const bf16_t qt = f2bf(qs * __expf(b));
;           QT[((size_t)cid * 32 + t) * 128 + k] = qt;
;           sQ[t * 136 + k] = qt;
;           sK[t * 136 + k] = f2bf(kk[j] * __expf(fminf(-b, 80.f)));
;           bt[j] = kk[j] * __expf(bend - b);
	ds_read2st64_b32 v[54:55], v18 offset0:68 offset1:70
	s_waitcnt lgkmcnt(0)
	v_cndmask_b32_e64 v53, v54, 0, s[4:5]
	v_add_f32_e32 v101, v57, v53
	v_mul_f32_e32 v57, 0xbfb8aa3b, v56
	v_exp_f32_e32 v57, v57
	v_add_f32_e32 v86, v86, v53
	v_mul_f32_e32 v103, 0x3fb8aa3b, v86
	v_exp_f32_e32 v103, v103
	v_add_f32_e32 v57, 1.0, v57
	v_rcp_f32_e32 v57, v57
	v_mul_f32_e32 v79, v79, v103
	v_bfe_u32 v103, v79, 16, 1
	v_mul_f32_e32 v56, v57, v56
	v_mul_f32_e32 v57, 0x3fb8aa3b, v101
	v_exp_f32_e32 v57, v57
	v_add3_u32 v79, v79, v103, s33
	v_min_f32_e64 v103, -v86, s9
	v_mul_f32_e32 v103, 0x3fb8aa3b, v103
	v_mul_f32_e32 v56, v56, v57
	v_bfe_u32 v57, v56, 16, 1
	v_add3_u32 v56, v56, v57, s33
	v_lshrrev_b32_e32 v102, 16, v56
	v_lshl_add_u64 v[56:57], s[2:3], 0, v[28:29]
	global_store_short v[56:57], v102, off offset:-1792
	ds_write_b16 v60, v102
	v_min_f32_e64 v102, -v101, s9
	v_mul_f32_e32 v102, 0x3fb8aa3b, v102
	v_exp_f32_e32 v102, v102
	v_exp_f32_e32 v103, v103
	v_lshrrev_b32_e32 v79, 16, v79
	global_store_short v[56:57], v79, off offset:-1536
	v_mul_f32_e32 v8, v6, v102
	v_bfe_u32 v9, v8, 16, 1
	v_add3_u32 v8, v8, v9, s33
	ds_write_b16_d16_hi v60, v8 offset:8704
	ds_write_b16 v61, v79
	v_mul_f32_e32 v8, v7, v103
	v_bfe_u32 v9, v8, 16, 1
	v_add3_u32 v8, v8, v9, s33
	ds_write_b16_d16_hi v61, v8 offset:8704
	v_mul_f32_e32 v8, 0xbfb8aa3b, v83
	v_exp_f32_e32 v8, v8
	v_add_f32_e32 v79, v89, v53
	v_mul_f32_e32 v9, 0x3fb8aa3b, v79
	v_exp_f32_e32 v9, v9
	v_add_f32_e32 v8, 1.0, v8
	v_rcp_f32_e32 v8, v8
	s_nop 0
	v_mul_f32_e32 v8, v8, v83
	v_mul_f32_e32 v8, v8, v9
	v_bfe_u32 v9, v8, 16, 1
	v_add3_u32 v8, v8, v9, s33
	v_lshrrev_b32_e32 v8, 16, v8
	global_store_short v[56:57], v8, off offset:-1280
	ds_write_b16 v62, v8
	v_min_f32_e64 v8, -v79, s9
	v_mul_f32_e32 v8, 0x3fb8aa3b, v8
	v_exp_f32_e32 v89, v8
	v_mul_f32_e32 v8, 0xbfb8aa3b, v88
	v_exp_f32_e32 v8, v8
	v_add_f32_e32 v83, v92, v53
	v_mul_f32_e32 v9, 0x3fb8aa3b, v83
	v_exp_f32_e32 v9, v9
	v_add_f32_e32 v8, 1.0, v8
	v_rcp_f32_e32 v8, v8
	s_nop 0
	v_mul_f32_e32 v8, v8, v88
	v_mul_f32_e32 v8, v8, v9
	v_bfe_u32 v9, v8, 16, 1
	v_add3_u32 v8, v8, v9, s33
	v_lshrrev_b32_e32 v88, 16, v8
	v_min_f32_e64 v8, -v83, s9
	v_mul_f32_e32 v8, 0x3fb8aa3b, v8
	v_exp_f32_e32 v92, v8
	v_pk_mul_f32 v[8:9], v[0:1], v[36:37] op_sel_hi:[0,1]
	v_pk_mul_f32 v[8:9], v[8:9], v[34:35]
	global_store_short v[56:57], v88, off offset:-1024
	v_mul_f32_e32 v34, v8, v89
	v_bfe_u32 v35, v34, 16, 1
	v_add3_u32 v34, v34, v35, s33
	ds_write_b16_d16_hi v62, v34 offset:8704
	ds_write_b16 v63, v88
	v_mul_f32_e32 v34, v9, v92
	v_bfe_u32 v35, v34, 16, 1
	v_add3_u32 v34, v34, v35, s33
	ds_write_b16_d16_hi v63, v34 offset:8704
	v_mul_f32_e32 v34, 0xbfb8aa3b, v81
	v_exp_f32_e32 v34, v34
	v_add_f32_e32 v36, v87, v53
	v_mul_f32_e32 v35, 0x3fb8aa3b, v36
	v_exp_f32_e32 v35, v35
	v_add_f32_e32 v34, 1.0, v34
	v_rcp_f32_e32 v34, v34
	v_add_f32_e32 v37, v82, v53
	v_mul_f32_e32 v34, v34, v81
	v_mul_f32_e32 v34, v34, v35
	v_bfe_u32 v35, v34, 16, 1
	v_add3_u32 v34, v34, v35, s33
	v_mul_f32_e32 v35, 0xbfb8aa3b, v77
	v_exp_f32_e32 v35, v35
	v_lshrrev_b32_e32 v34, 16, v34
	global_store_short v[56:57], v34, off offset:-768
	ds_write_b16 v64, v34
	v_add_f32_e32 v35, 1.0, v35
	v_rcp_f32_e32 v35, v35
	v_min_f32_e64 v34, -v36, s9
	v_mul_f32_e32 v34, 0x3fb8aa3b, v34
	v_exp_f32_e32 v34, v34
	v_mul_f32_e32 v35, v35, v77
	v_mul_f32_e32 v77, 0x3fb8aa3b, v37
	v_exp_f32_e32 v77, v77
	v_mul_f32_e32 v32, v14, v34
	v_bfe_u32 v33, v32, 16, 1
	v_add3_u32 v32, v32, v33, s33
	v_mul_f32_e32 v35, v35, v77
	v_bfe_u32 v77, v35, 16, 1
	v_add3_u32 v35, v35, v77, s33
	v_min_f32_e64 v77, -v37, s9
	v_mul_f32_e32 v77, 0x3fb8aa3b, v77
	v_exp_f32_e32 v77, v77
	v_lshrrev_b32_e32 v35, 16, v35
	global_store_short v[56:57], v35, off offset:-512
	ds_write_b16_d16_hi v64, v32 offset:8704
	ds_write_b16 v65, v35
	v_mul_f32_e32 v32, v15, v77
	v_bfe_u32 v33, v32, 16, 1
	v_add3_u32 v32, v32, v33, s33
	ds_write_b16_d16_hi v65, v32 offset:8704
	v_mul_f32_e32 v32, 0xbfb8aa3b, v95
	v_exp_f32_e32 v32, v32
	v_add_f32_e32 v77, v97, v53
	v_mul_f32_e32 v33, 0x3fb8aa3b, v77
	v_exp_f32_e32 v33, v33
	v_add_f32_e32 v32, 1.0, v32
	v_rcp_f32_e32 v32, v32
	v_add_f32_e32 v81, v96, v53
	v_mul_f32_e32 v32, v32, v95
	v_mul_f32_e32 v32, v32, v33
	v_bfe_u32 v33, v32, 16, 1
	v_add3_u32 v32, v32, v33, s33
	v_lshrrev_b32_e32 v32, 16, v32
	global_store_short v[56:57], v32, off offset:-256
	ds_write_b16 v66, v32
	v_min_f32_e64 v32, -v77, s9
	v_mul_f32_e32 v32, 0x3fb8aa3b, v32
	v_exp_f32_e32 v34, v32
	v_mul_f32_e32 v32, 0xbfb8aa3b, v94
	v_exp_f32_e32 v32, v32
	v_mul_f32_e32 v33, 0x3fb8aa3b, v81
	v_exp_f32_e32 v33, v33
	v_add_f32_e32 v32, 1.0, v32
	v_rcp_f32_e32 v32, v32
	s_nop 0
	v_mul_f32_e32 v32, v32, v94
	v_mul_f32_e32 v32, v32, v33
	v_bfe_u32 v33, v32, 16, 1
	v_add3_u32 v32, v32, v33, s33
	v_lshrrev_b32_e32 v35, 16, v32
	v_min_f32_e64 v32, -v81, s9
	v_mul_f32_e32 v32, 0x3fb8aa3b, v32
	v_exp_f32_e32 v82, v32
	v_pk_mul_f32 v[32:33], v[0:1], v[44:45] op_sel_hi:[0,1]
	v_pk_mul_f32 v[32:33], v[32:33], v[42:43]
	global_store_short v[56:57], v35, off
	v_mul_f32_e32 v34, v32, v34
	v_bfe_u32 v42, v34, 16, 1
	v_add3_u32 v34, v34, v42, s33
	ds_write_b16_d16_hi v66, v34 offset:8704
	ds_write_b16 v67, v35
	v_mul_f32_e32 v34, v33, v82
	v_bfe_u32 v35, v34, 16, 1
	v_add3_u32 v34, v34, v35, s33
	ds_write_b16_d16_hi v67, v34 offset:8704
	v_mul_f32_e32 v34, 0xbfb8aa3b, v90
	v_exp_f32_e32 v34, v34
	v_add_f32_e32 v42, v93, v53
	v_mul_f32_e32 v35, 0x3fb8aa3b, v42
	v_exp_f32_e32 v35, v35
; DEVI bf16_t f2bf(float f) { uint32_t u = __float_as_uint(f); u += 0x7fffu + ((u >> 16) & 1u); return (bf16_t)(u >> 16); }
; DEVI uint32_t pack2(float lo, float hi) { f32x2_t v = {lo, hi}; bf16x2_t b = __builtin_convertvector(v, bf16x2_t); return __builtin_bit_cast(uint32_t, b); }
; DEVI void phase_p2(const int TIDX, const int BIDX, const int GDIM, KAP KA, unsigned char* WSB, float* OUTB, int l, unsigned char* smem) {
;     ...
;         for (int j = 0; j < 16; ++j) {
;           const int t = half * 16 + j;
;           const float b = bt[j] + off;
;           const float qs = qv[j] * __builtin_amdgcn_rcpf(1.f + __expf(-qv[j]));
;           const bf16_t qt = f2bf(qs * __expf(b));
;           QT[((size_t)cid * 32 + t) * 128 + k] = qt;
;           sQ[t * 136 + k] = qt;
;           sK[t * 136 + k] = f2bf(kk[j] * __expf(fminf(-b, 80.f)));
;           bt[j] = kk[j] * __expf(bend - b);
;         }
; #pragma unroll
;         for (int j = 0; j < 8; ++j) pk[j] = pack2(bt[2 * j], bt[2 * j + 1]);
;         if (half == 0) EBp[(size_t)cid * 128 + k] = __expf(bend);
	v_add_f32_e32 v34, 1.0, v34
	v_rcp_f32_e32 v34, v34
	v_add_f32_e32 v43, v91, v53
	v_mul_f32_e32 v34, v34, v90
	v_mul_f32_e32 v34, v34, v35
	v_bfe_u32 v35, v34, 16, 1
	v_add3_u32 v34, v34, v35, s33
	v_lshrrev_b32_e32 v34, 16, v34
	global_store_short v[56:57], v34, off offset:256
	ds_write_b16 v68, v34
	v_min_f32_e64 v34, -v42, s9
	v_mul_f32_e32 v34, 0x3fb8aa3b, v34
	v_exp_f32_e32 v44, v34
	v_mul_f32_e32 v34, 0xbfb8aa3b, v84
	v_exp_f32_e32 v34, v34
	v_mul_f32_e32 v35, 0x3fb8aa3b, v43
	v_exp_f32_e32 v35, v35
	v_add_f32_e32 v34, 1.0, v34
	v_rcp_f32_e32 v34, v34
	s_nop 0
	v_mul_f32_e32 v34, v34, v84
	v_mul_f32_e32 v34, v34, v35
	v_bfe_u32 v35, v34, 16, 1
	v_add3_u32 v34, v34, v35, s33
	v_lshrrev_b32_e32 v45, 16, v34
	v_min_f32_e64 v34, -v43, s9
	v_mul_f32_e32 v34, 0x3fb8aa3b, v34
	v_exp_f32_e32 v82, v34
	v_pk_mul_f32 v[34:35], v[0:1], v[40:41] op_sel_hi:[0,1]
	v_pk_mul_f32 v[34:35], v[34:35], v[38:39]
	global_store_short v[56:57], v45, off offset:512
	v_mul_f32_e32 v38, v34, v44
	v_bfe_u32 v39, v38, 16, 1
	v_add3_u32 v38, v38, v39, s33
	ds_write_b16_d16_hi v68, v38 offset:8704
	ds_write_b16 v69, v45
	v_mul_f32_e32 v38, v35, v82
	v_bfe_u32 v39, v38, 16, 1
	v_add3_u32 v38, v38, v39, s33
	v_mul_f32_e32 v39, 0xbfb8aa3b, v78
	v_exp_f32_e32 v39, v39
	ds_write_b16_d16_hi v69, v38 offset:8704
	v_add_f32_e32 v38, v85, v53
	v_mul_f32_e32 v40, 0x3fb8aa3b, v38
	v_add_f32_e32 v39, 1.0, v39
	v_rcp_f32_e32 v39, v39
	v_exp_f32_e32 v40, v40
	v_mul_f32_e32 v41, 0xbfb8aa3b, v76
	v_exp_f32_e32 v41, v41
	v_mul_f32_e32 v39, v39, v78
	v_mul_f32_e32 v39, v39, v40
	v_bfe_u32 v40, v39, 16, 1
	v_add3_u32 v39, v39, v40, s33
	v_lshrrev_b32_e32 v39, 16, v39
	global_store_short v[56:57], v39, off offset:768
	ds_write_b16 v70, v39
	v_min_f32_e64 v39, -v38, s9
	v_mul_f32_e32 v39, 0x3fb8aa3b, v39
	v_exp_f32_e32 v40, v39
	v_add_f32_e32 v39, v80, v53
	v_add_f32_e32 v41, 1.0, v41
	v_rcp_f32_e32 v41, v41
	v_mul_f32_e32 v44, 0x3fb8aa3b, v39
	v_exp_f32_e32 v44, v44
	v_mul_f32_e32 v12, v10, v40
	v_mul_f32_e32 v41, v41, v76
	v_bfe_u32 v13, v12, 16, 1
	v_mul_f32_e32 v41, v41, v44
	v_bfe_u32 v44, v41, 16, 1
	v_add3_u32 v41, v41, v44, s33
	v_min_f32_e64 v44, -v39, s9
	v_mul_f32_e32 v44, 0x3fb8aa3b, v44
	v_exp_f32_e32 v44, v44
	v_lshrrev_b32_e32 v41, 16, v41
	v_add3_u32 v12, v12, v13, s33
	global_store_short v[56:57], v41, off offset:1024
	ds_write_b16_d16_hi v70, v12 offset:8704
	ds_write_b16 v71, v41
	v_mul_f32_e32 v12, v11, v44
	v_bfe_u32 v13, v12, 16, 1
	v_add3_u32 v12, v12, v13, s33
	v_mul_f32_e32 v13, 0xbfb8aa3b, v19
	v_exp_f32_e32 v13, v13
	ds_write_b16_d16_hi v71, v12 offset:8704
	v_add_f32_e32 v12, v52, v53
	v_mul_f32_e32 v40, 0xbfb8aa3b, v1
	v_add_f32_e32 v13, 1.0, v13
	v_rcp_f32_e32 v13, v13
	v_exp_f32_e32 v40, v40
	v_mov_b32_e32 v52, v54
	v_mul_f32_e32 v13, v13, v19
	v_mul_f32_e32 v19, 0x3fb8aa3b, v12
	v_exp_f32_e32 v19, v19
	v_add_f32_e32 v40, 1.0, v40
	v_rcp_f32_e32 v40, v40
	v_mul_f32_e32 v13, v13, v19
	v_bfe_u32 v19, v13, 16, 1
	v_add3_u32 v13, v13, v19, s33
	v_lshrrev_b32_e32 v13, 16, v13
	global_store_short v[56:57], v13, off offset:1280
	ds_write_b16 v72, v13
	v_min_f32_e64 v13, -v12, s9
	v_mul_f32_e32 v13, 0x3fb8aa3b, v13
	v_exp_f32_e32 v19, v13
	v_add_f32_e32 v13, v53, v50
	v_mul_f32_e32 v1, v40, v1
	v_mul_f32_e32 v40, 0x3fb8aa3b, v13
	v_exp_f32_e32 v40, v40
	v_mov_b32_e32 v50, v55
	v_mul_f32_e32 v1, v1, v40
	v_bfe_u32 v40, v1, 16, 1
	v_add3_u32 v1, v1, v40, s33
	v_lshrrev_b32_e32 v1, 16, v1
	v_min_f32_e64 v40, -v13, s9
	v_mul_f32_e32 v40, 0x3fb8aa3b, v40
	v_pk_mul_f32 v[4:5], v[0:1], v[4:5] op_sel_hi:[0,1]
	v_exp_f32_e32 v40, v40
	v_pk_mul_f32 v[2:3], v[4:5], v[2:3]
	global_store_short v[56:57], v1, off offset:1536
	v_mul_f32_e32 v4, v2, v19
	v_bfe_u32 v5, v4, 16, 1
	v_add3_u32 v4, v4, v5, s33
	ds_write_b16_d16_hi v72, v4 offset:8704
	ds_write_b16 v73, v1
	v_mul_f32_e32 v1, v3, v40
	v_bfe_u32 v4, v1, 16, 1
	v_add3_u32 v1, v1, v4, s33
	ds_write_b16_d16_hi v73, v1 offset:8704
	v_mul_f32_e32 v1, 0xbfb8aa3b, v98
	v_exp_f32_e32 v1, v1
	v_add_f32_e32 v19, v53, v99
	v_mul_f32_e32 v4, 0x3fb8aa3b, v19
	v_exp_f32_e32 v4, v4
	v_add_f32_e32 v1, 1.0, v1
	v_rcp_f32_e32 v1, v1
	s_nop 0
	v_mul_f32_e32 v1, v1, v98
	v_mul_f32_e32 v1, v1, v4
	v_bfe_u32 v4, v1, 16, 1
	v_add3_u32 v1, v1, v4, s33
	v_lshrrev_b32_e32 v1, 16, v1
	global_store_short v[56:57], v1, off offset:1792
	ds_write_b16 v74, v1
	v_min_f32_e64 v1, -v19, s9
	v_mul_f32_e32 v1, 0x3fb8aa3b, v1
	v_exp_f32_e32 v44, v1
	v_mul_f32_e32 v1, 0xbfb8aa3b, v100
	v_exp_f32_e32 v1, v1
	v_pk_add_f32 v[4:5], v[52:53], v[50:51]
	v_add_f32_e32 v1, 1.0, v1
	v_rcp_f32_e32 v1, v1
	v_mul_f32_e32 v40, 0x3fb8aa3b, v5
	v_exp_f32_e32 v40, v40
	v_mul_f32_e32 v1, v1, v100
	v_mul_f32_e32 v1, v1, v40
	v_bfe_u32 v40, v1, 16, 1
	v_add3_u32 v1, v1, v40, s33
	v_lshrrev_b32_e32 v45, 16, v1
	v_min_f32_e64 v1, -v5, s9
	v_lshl_add_u64 v[40:41], s[2:3], 0, v[26:27]
	v_mul_f32_e32 v1, 0x3fb8aa3b, v1
	global_store_short v[40:41], v45, off
	v_exp_f32_e32 v40, v1
	v_pk_mul_f32 v[0:1], v[0:1], v[48:49] op_sel_hi:[0,1]
	v_pk_mul_f32 v[0:1], v[0:1], v[46:47]
	s_nop 0
	v_mul_f32_e32 v41, v0, v44
	v_bfe_u32 v44, v41, 16, 1
	v_add3_u32 v41, v41, v44, s33
	v_mul_f32_e32 v40, v1, v40
	ds_write_b16_d16_hi v74, v41 offset:8704
	ds_write_b16 v75, v45
	v_bfe_u32 v41, v40, 16, 1
	v_add3_u32 v40, v40, v41, s33
	ds_write_b16_d16_hi v75, v40 offset:8704
	s_and_saveexec_b64 s[44:45], s[4:5]
	s_cbranch_execz .LBB0_382
	v_mul_f32_e32 v40, 0x3fb8aa3b, v4
	v_exp_f32_e32 v40, v40
	global_store_dword v[22:23], v40, off
